# MLA flash loop: next K/V tile's global loads issued at tile start, LDS staging writes moved from the tile end into mid-PV (other buffer is free all tile)
# speedup vs baseline: 1.0022x; 1.0022x over previous
; __device__ __forceinline__ unsigned cvt_pk_bf16(float lo, float hi) { const f32x2c f = {lo, hi}; return __builtin_bit_cast(unsigned, __builtin_convertvector(f, bf16x2c)); }
; #define LASP __attribute__((address_space(3)))
; template <int DQK>
; __device__ __forceinline__ void flash_item(unsigned char* smem, const bf16_t* Q, int qs, const bf16_t* K0, const bf16_t* V0, int n0, const bf16_t* K1, const bf16_t* V1, int n1, int ks, int vs, bf16_t* Oo, int os, float shift) {
;     ...
;         for (int qg = 0; qg < 2; ++qg) {
;             float ps = 0.f;
; #pragma unroll
;             for (int kg = 0; kg < NKG; ++kg)
; #pragma unroll
;                 for (int j = 0; j < 4; ++j) { const float p = __builtin_amdgcn_exp2f(s[kg][qg][j]); s[kg][qg][j] = p; ps += p; }
;             lsum[qg] += ps;
;         }
; #pragma unroll
;         for (int kp = 0; kp < NKP; ++kp) {
;             bf16x8_t pb[2];
; #pragma unroll
;             for (int qg = 0; qg < 2; ++qg) {
;                 const f32x4_t a = s[2 * kp][qg], b = s[2 * kp + 1][qg];
;                 u32x4_t pk; pk.x = pg8::cvt_pk_bf16(a[0], a[1]); pk.y = pg8::cvt_pk_bf16(a[2], a[3]); pk.z = pg8::cvt_pk_bf16(b[0], b[1]); pk.w = pg8::cvt_pk_bf16(b[2], b[3]);
;                 pb[qg] = __builtin_bit_cast(bf16x8_t, pk);
;             }
; #pragma unroll
;             for (int dg = 0; dg < 4; ++dg) {
;                 LASP unsigned char* va = ls + VOFF + (32 * kp + 4 * fq + (fr >> 2)) * VR + (16 * dg + 4 * (fr & 3)) * 2;
;                 const s16x4 v0 = __builtin_amdgcn_ds_read_tr16_b64_v4i16((LASP s16x4*)va);
;                 const s16x4 v1 = __builtin_amdgcn_ds_read_tr16_b64_v4i16((LASP s16x4*)(va + 16 * VR));
;                 const bf16x8_t vf = __builtin_shufflevector(v0, v1, 0, 1, 2, 3, 4, 5, 6, 7);
;                 o[dg][0] = __builtin_amdgcn_mfma_f32_16x16x32_bf16(vf, pb[0], o[dg][0], 0, 0, 0);
;                 o[dg][1] = __builtin_amdgcn_mfma_f32_16x16x32_bf16(vf, pb[1], o[dg][1], 0, 0, 0);
;             }
.LBB0_831:
	ds_read_b64_tr_b16 v[182:183], v163 offset:35072
	ds_read_b64_tr_b16 v[180:181], v163 offset:32768
	ds_read_b64_tr_b16 v[184:185], v163 offset:32832
	ds_read_b64_tr_b16 v[186:187], v163 offset:35136
	ds_read_b64_tr_b16 v[188:189], v163 offset:32864
	ds_read_b64_tr_b16 v[190:191], v163 offset:35168
	ds_read_b64_tr_b16 v[192:193], v163 offset:32800
	ds_read_b64_tr_b16 v[194:195], v163 offset:35104
	ds_read_b64_tr_b16 v[196:197], v163 offset:37376
	ds_read_b64_tr_b16 v[198:199], v163 offset:39680
	ds_read_b64_tr_b16 v[200:201], v163 offset:37408
	ds_read_b64_tr_b16 v[202:203], v163 offset:39712
	s_nop 0
	v_exp_f32_e32 v148, v138
	v_exp_f32_e32 v149, v139
	v_exp_f32_e32 v150, v140
	v_exp_f32_e32 v151, v141
	v_add_f32_e32 v138, 0, v148
	v_exp_f32_e32 v152, v134
	v_add_f32_e32 v138, v149, v138
	v_exp_f32_e32 v153, v135
	v_add_f32_e32 v138, v150, v138
	v_exp_f32_e32 v166, v136
	v_add_f32_e32 v138, v151, v138
	v_exp_f32_e32 v167, v137
	v_add_f32_e32 v134, v152, v138
	v_exp_f32_e32 v136, v130
	v_add_f32_e32 v134, v153, v134
	v_exp_f32_e32 v137, v131
	v_add_f32_e32 v134, v166, v134
	v_exp_f32_e32 v138, v132
	v_add_f32_e32 v134, v167, v134
	v_exp_f32_e32 v139, v133
	v_add_f32_e32 v130, v136, v134
	v_exp_f32_e32 v140, v126
	v_add_f32_e32 v130, v137, v130
	v_exp_f32_e32 v141, v127
	v_add_f32_e32 v130, v138, v130
	v_exp_f32_e32 v164, v128
	v_add_f32_e32 v130, v139, v130
	v_exp_f32_e32 v165, v129
	v_add_f32_e32 v126, v140, v130
	v_exp_f32_e32 v130, v110
	v_add_f32_e32 v126, v141, v126
	v_exp_f32_e32 v131, v111
	v_add_f32_e32 v126, v164, v126
	v_exp_f32_e32 v132, v112
	v_add_f32_e32 v126, v165, v126
	v_exp_f32_e32 v133, v113
	v_add_f32_e32 v110, v130, v126
	v_exp_f32_e32 v134, v118
	v_add_f32_e32 v110, v131, v110
	v_exp_f32_e32 v135, v119
	v_exp_f32_e32 v102, v102
	v_add_f32_e32 v110, v132, v110
	v_exp_f32_e32 v103, v103
	v_add_f32_e32 v110, v133, v110
	v_exp_f32_e32 v104, v104
	v_add_f32_e32 v110, v134, v110
	v_exp_f32_e32 v105, v105
	v_add_f32_e32 v147, v135, v110
	v_add_f32_e32 v110, 0, v102
	v_exp_f32_e32 v168, v86
	v_add_f32_e32 v110, v103, v110
	v_exp_f32_e32 v169, v87
	v_add_f32_e32 v110, v104, v110
	v_exp_f32_e32 v170, v88
	v_add_f32_e32 v110, v105, v110
	v_exp_f32_e32 v171, v89
	v_add_f32_e32 v86, v168, v110
	v_exp_f32_e32 v172, v78
	v_add_f32_e32 v86, v169, v86
	v_exp_f32_e32 v173, v79
	v_add_f32_e32 v86, v170, v86
	v_exp_f32_e32 v174, v80
	v_add_f32_e32 v86, v171, v86
	v_exp_f32_e32 v175, v81
	v_add_f32_e32 v78, v172, v86
	v_exp_f32_e32 v176, v90
	v_add_f32_e32 v78, v173, v78
	v_exp_f32_e32 v177, v91
	v_add_f32_e32 v78, v174, v78
	v_exp_f32_e32 v178, v92
	v_add_f32_e32 v78, v175, v78
	v_exp_f32_e32 v179, v93
	v_add_f32_e32 v78, v176, v78
	v_exp_f32_e32 v86, v82
	v_add_f32_e32 v78, v177, v78
	v_exp_f32_e32 v87, v83
	v_add_f32_e32 v78, v178, v78
	v_exp_f32_e32 v88, v84
	v_add_f32_e32 v78, v179, v78
	v_exp_f32_e32 v89, v85
	v_add_f32_e32 v78, v86, v78
	v_exp_f32_e32 v90, v98
	v_add_f32_e32 v78, v87, v78
	v_exp_f32_e32 v91, v99
	v_exp_f32_e32 v127, v120
	v_add_f32_e32 v78, v88, v78
	v_exp_f32_e32 v126, v100
	v_exp_f32_e32 v129, v121
	v_add_f32_e32 v78, v89, v78
	v_exp_f32_e32 v128, v101
	v_exp_f32_e32 v111, v114
	v_add_f32_e32 v78, v90, v78
	v_exp_f32_e32 v110, v94
	v_exp_f32_e32 v115, v115
	v_add_f32_e32 v146, v91, v78
	v_exp_f32_e32 v114, v95
	v_exp_f32_e32 v113, v116
	v_exp_f32_e32 v112, v96
	v_pk_add_f32 v[78:79], v[126:127], v[146:147]
	v_exp_f32_e32 v119, v117
	v_exp_f32_e32 v118, v97
	v_pk_add_f32 v[78:79], v[128:129], v[78:79]
	v_exp_f32_e32 v117, v122
	v_exp_f32_e32 v116, v106
	v_pk_add_f32 v[78:79], v[110:111], v[78:79]
	v_exp_f32_e32 v123, v123
	v_exp_f32_e32 v122, v107
	v_pk_add_f32 v[78:79], v[114:115], v[78:79]
	v_exp_f32_e32 v121, v124
	v_exp_f32_e32 v120, v108
	v_pk_add_f32 v[78:79], v[112:113], v[78:79]
	v_exp_f32_e32 v125, v125
	v_exp_f32_e32 v124, v109
	v_pk_add_f32 v[78:79], v[118:119], v[78:79]
	v_pk_add_f32 v[78:79], v[116:117], v[78:79]
	v_cvt_pk_bf16_f32 v82, v148, v149
	v_pk_add_f32 v[78:79], v[122:123], v[78:79]
	v_cvt_pk_bf16_f32 v83, v150, v151
	v_pk_add_f32 v[78:79], v[120:121], v[78:79]
	v_cvt_pk_bf16_f32 v84, v152, v153
	v_pk_add_f32 v[78:79], v[124:125], v[78:79]
	v_cvt_pk_bf16_f32 v85, v166, v167
	v_pk_add_f32 v[156:157], v[156:157], v[78:79]
	v_cvt_pk_bf16_f32 v78, v102, v103
	v_cvt_pk_bf16_f32 v79, v104, v105
	v_cvt_pk_bf16_f32 v80, v168, v169
	v_cvt_pk_bf16_f32 v81, v170, v171
	ds_read_b64_tr_b16 v[204:205], v163 offset:37440
	ds_read_b64_tr_b16 v[206:207], v163 offset:39744
	s_waitcnt lgkmcnt(12)
	v_mfma_f32_16x16x32_bf16 v[62:65], v[180:183], v[82:85], v[62:65]
	v_lshl_add_u64 v[158:159], v[158:159], 0, s[36:37]
	v_lshl_add_u64 v[160:161], v[160:161], 0, s[14:15]
	v_mfma_f32_16x16x32_bf16 v[58:61], v[180:183], v[78:81], v[58:61]
	s_cmp_lg_u32 s27, s29
	ds_read_b64_tr_b16 v[180:181], v163 offset:37472
	ds_read_b64_tr_b16 v[182:183], v163 offset:39776
	s_waitcnt lgkmcnt(12)
	v_mfma_f32_16x16x32_bf16 v[70:73], v[184:187], v[82:85], v[70:73]
	v_mfma_f32_16x16x32_bf16 v[6:9], v[184:187], v[78:81], v[6:9]
	ds_read_b64_tr_b16 v[184:185], v163 offset:41984
	ds_read_b64_tr_b16 v[186:187], v163 offset:44288
	s_waitcnt lgkmcnt(12)
	v_mfma_f32_16x16x32_bf16 v[66:69], v[188:191], v[82:85], v[66:69]
	v_mfma_f32_16x16x32_bf16 v[10:13], v[188:191], v[78:81], v[10:13]
	ds_read_b64_tr_b16 v[188:189], v163 offset:42016
	ds_read_b64_tr_b16 v[190:191], v163 offset:44320
	s_waitcnt lgkmcnt(12)
	v_mfma_f32_16x16x32_bf16 v[74:77], v[192:195], v[82:85], v[74:77]
	v_cvt_pk_bf16_f32 v82, v172, v173
	v_cvt_pk_bf16_f32 v83, v174, v175
	v_cvt_pk_bf16_f32 v84, v176, v177
	v_mfma_f32_16x16x32_bf16 v[2:5], v[192:195], v[78:81], v[2:5]
	v_cvt_pk_bf16_f32 v78, v136, v137
	v_cvt_pk_bf16_f32 v79, v138, v139
	v_cvt_pk_bf16_f32 v80, v140, v141
	v_cvt_pk_bf16_f32 v81, v164, v165
	v_cvt_pk_bf16_f32 v85, v178, v179
	ds_read_b64_tr_b16 v[192:193], v163 offset:42048
	ds_read_b64_tr_b16 v[194:195], v163 offset:44352
	s_waitcnt lgkmcnt(12)
	v_mfma_f32_16x16x32_bf16 v[62:65], v[196:199], v[78:81], v[62:65]
	v_mfma_f32_16x16x32_bf16 v[58:61], v[196:199], v[82:85], v[58:61]
	ds_read_b64_tr_b16 v[196:197], v163 offset:42080
	ds_read_b64_tr_b16 v[198:199], v163 offset:44384
	s_waitcnt lgkmcnt(12)
	v_mfma_f32_16x16x32_bf16 v[74:77], v[200:203], v[78:81], v[74:77]
	v_mfma_f32_16x16x32_bf16 v[2:5], v[200:203], v[82:85], v[2:5]
	ds_read_b64_tr_b16 v[200:201], v163 offset:46592
	ds_read_b64_tr_b16 v[202:203], v163 offset:48896
	s_waitcnt lgkmcnt(12)
	v_mfma_f32_16x16x32_bf16 v[70:73], v[204:207], v[78:81], v[70:73]
	v_mfma_f32_16x16x32_bf16 v[6:9], v[204:207], v[82:85], v[6:9]
	ds_read_b64_tr_b16 v[204:205], v163 offset:46624
	ds_read_b64_tr_b16 v[206:207], v163 offset:48928
	s_waitcnt lgkmcnt(12)
	v_mfma_f32_16x16x32_bf16 v[10:13], v[180:183], v[82:85], v[10:13]
	s_cbranch_scc0 .Lmla_w_skip
; __device__ __forceinline__ unsigned cvt_pk_bf16(float lo, float hi) { const f32x2c f = {lo, hi}; return __builtin_bit_cast(unsigned, __builtin_convertvector(f, bf16x2c)); }
; #define LASP __attribute__((address_space(3)))
; template <int DQK>
; __device__ __forceinline__ void flash_item(unsigned char* smem, const bf16_t* Q, int qs, const bf16_t* K0, const bf16_t* V0, int n0, const bf16_t* K1, const bf16_t* V1, int n1, int ks, int vs, bf16_t* Oo, int os, float shift) {
;     ...
;     for (int t = 0; t < ntiles; ++t) {
;         __syncthreads();
; #pragma unroll
;         for (int c = 0; c < NKC; ++c) *(LASP u32x4_t*)(ls + (tid >> 2) * KR + ((tid & 3) + 4 * c) * 16) = kreg[c];
; #pragma unroll
;         for (int c = 0; c < NVC; ++c) *(LASP u32x4_t*)(ls + VOFF + ((tid >> 3) + 64 * c) * VR + (tid & 7) * 16) = vreg[c];
;         __syncthreads();
;         f32x4_t s[NKG][2];
; #pragma unroll
;         for (int kg = 0; kg < NKG; ++kg) { s[kg][0] = (f32x4_t){nsh, nsh, nsh, nsh}; s[kg][1] = (f32x4_t){nsh, nsh, nsh, nsh}; }
; #pragma unroll
;         for (int kk = 0; kk < NKK; ++kk) {
; #pragma unroll
;             for (int kg = 0; kg < NKG; ++kg) {
;                 const bf16x8_t kf = *(const LASP bf16x8_t*)(ls + (kg * 16 + fr) * KR + (kk * 32 + fq * 8) * 2);
;     ...
;                 u32x4_t pk; pk.x = pg8::cvt_pk_bf16(a[0], a[1]); pk.y = pg8::cvt_pk_bf16(a[2], a[3]); pk.z = pg8::cvt_pk_bf16(b[0], b[1]); pk.w = pg8::cvt_pk_bf16(b[2], b[3]);
;                 pb[qg] = __builtin_bit_cast(bf16x8_t, pk);
;             }
; #pragma unroll
;             for (int dg = 0; dg < 4; ++dg) {
;                 LASP unsigned char* va = ls + VOFF + (32 * kp + 4 * fq + (fr >> 2)) * VR + (16 * dg + 4 * (fr & 3)) * 2;
;                 const s16x4 v0 = __builtin_amdgcn_ds_read_tr16_b64_v4i16((LASP s16x4*)va);
;                 const s16x4 v1 = __builtin_amdgcn_ds_read_tr16_b64_v4i16((LASP s16x4*)(va + 16 * VR));
;                 const bf16x8_t vf = __builtin_shufflevector(v0, v1, 0, 1, 2, 3, 4, 5, 6, 7);
;                 o[dg][0] = __builtin_amdgcn_mfma_f32_16x16x32_bf16(vf, pb[0], o[dg][0], 0, 0, 0);
;                 o[dg][1] = __builtin_amdgcn_mfma_f32_16x16x32_bf16(vf, pb[1], o[dg][1], 0, 0, 0);
;             }
	v_xor_b32_e32 v1, 0x10000, v1
	v_xor_b32_e32 v143, 0x10000, v143
	s_waitcnt vmcnt(2)
	ds_write_b128 v1, v[42:45]
	ds_write_b128 v1, v[38:41] offset:64
	ds_write_b128 v1, v[46:49] offset:128
	s_waitcnt vmcnt(1)
	ds_write_b128 v143, v[50:53] offset:32768
	s_waitcnt vmcnt(0)
	ds_write_b128 v143, v[54:57] offset:41984
.Lmla_w_skip:
	v_cvt_pk_bf16_f32 v82, v86, v87
	v_cvt_pk_bf16_f32 v83, v88, v89
	v_mfma_f32_16x16x32_bf16 v[66:69], v[180:183], v[78:81], v[66:69]
	v_cvt_pk_bf16_f32 v78, v130, v131
	v_cvt_pk_bf16_f32 v79, v132, v133
	v_cvt_pk_bf16_f32 v80, v134, v135
	v_cvt_pk_bf16_f32 v81, v127, v129
	v_cvt_pk_bf16_f32 v84, v90, v91
	v_cvt_pk_bf16_f32 v85, v126, v128
	ds_read_b64_tr_b16 v[180:181], v163 offset:46656
	ds_read_b64_tr_b16 v[182:183], v163 offset:48960
	s_waitcnt lgkmcnt(12)
	v_mfma_f32_16x16x32_bf16 v[62:65], v[184:187], v[78:81], v[62:65]
	v_mfma_f32_16x16x32_bf16 v[58:61], v[184:187], v[82:85], v[58:61]
	ds_read_b64_tr_b16 v[184:185], v163 offset:46688
	ds_read_b64_tr_b16 v[186:187], v163 offset:48992
	s_waitcnt lgkmcnt(12)
	v_mfma_f32_16x16x32_bf16 v[74:77], v[188:191], v[78:81], v[74:77]
	v_mfma_f32_16x16x32_bf16 v[2:5], v[188:191], v[82:85], v[2:5]
	s_waitcnt lgkmcnt(10)
	v_mfma_f32_16x16x32_bf16 v[70:73], v[192:195], v[78:81], v[70:73]
	v_mfma_f32_16x16x32_bf16 v[6:9], v[192:195], v[82:85], v[6:9]
	s_waitcnt lgkmcnt(8)
	v_mfma_f32_16x16x32_bf16 v[66:69], v[196:199], v[78:81], v[66:69]
	v_cvt_pk_bf16_f32 v78, v111, v115
	v_cvt_pk_bf16_f32 v79, v113, v119
	v_cvt_pk_bf16_f32 v80, v117, v123
	v_mfma_f32_16x16x32_bf16 v[10:13], v[196:199], v[82:85], v[10:13]
	v_cvt_pk_bf16_f32 v81, v121, v125
	v_cvt_pk_bf16_f32 v82, v110, v114
	v_cvt_pk_bf16_f32 v83, v112, v118
	v_cvt_pk_bf16_f32 v84, v116, v122
	v_cvt_pk_bf16_f32 v85, v120, v124
	s_waitcnt lgkmcnt(6)
	v_mfma_f32_16x16x32_bf16 v[62:65], v[200:203], v[78:81], v[62:65]
	v_mfma_f32_16x16x32_bf16 v[58:61], v[200:203], v[82:85], v[58:61]
	s_waitcnt lgkmcnt(4)
	v_mfma_f32_16x16x32_bf16 v[74:77], v[204:207], v[78:81], v[74:77]
	v_mfma_f32_16x16x32_bf16 v[2:5], v[204:207], v[82:85], v[2:5]
	s_waitcnt lgkmcnt(2)
	v_mfma_f32_16x16x32_bf16 v[70:73], v[180:183], v[78:81], v[70:73]
	v_mfma_f32_16x16x32_bf16 v[6:9], v[180:183], v[82:85], v[6:9]
	s_waitcnt lgkmcnt(0)
	v_mfma_f32_16x16x32_bf16 v[66:69], v[184:187], v[78:81], v[66:69]
	v_mfma_f32_16x16x32_bf16 v[10:13], v[184:187], v[82:85], v[10:13]
	s_cbranch_scc0 .LBB0_834
	v_xor_b32_e32 v162, 0x10000, v162
	v_xor_b32_e32 v163, 0x10000, v163
	s_waitcnt lgkmcnt(0)
	s_barrier
.LBB0_832:
	ds_read_b128 v[180:183], v162
	ds_read_b128 v[184:187], v162 offset:3328
	ds_read_b128 v[188:191], v162 offset:6656
	ds_read_b128 v[192:195], v162 offset:9984
	ds_read_b128 v[196:199], v162 offset:13312
	ds_read_b128 v[200:203], v162 offset:16640
	ds_read_b128 v[204:207], v162 offset:19968
	ds_read_b128 v[212:215], v162 offset:23296
	ds_read_b128 v[224:227], v162 offset:64
	ds_read_b128 v[228:231], v162 offset:3392
	v_mov_b64_e32 v[84:85], s[46:47]
	v_mov_b64_e32 v[82:83], s[44:45]
	s_add_i32 s29, s29, 1
	s_cmp_ge_u32 s29, s27
	s_cbranch_scc1 .Lmla_ld_skip
	v_lshl_add_u64 v[54:55], s[56:57], 0, v[158:159]
	v_add_co_u32_e32 v50, vcc, 0x1bc98000, v54
	v_lshl_add_u64 v[46:47], s[56:57], 0, v[160:161]
	s_nop 0
	v_addc_co_u32_e32 v51, vcc, 0, v55, vcc
	v_add_co_u32_e32 v54, vcc, 0x1bca4000, v54
	global_load_dwordx4 v[42:45], v[46:47], off offset:-64
	global_load_dwordx4 v[38:41], v[46:47], off
	v_addc_co_u32_e32 v55, vcc, 0, v55, vcc
	global_load_dwordx4 v[46:49], v[46:47], off offset:64
	s_nop 0
	global_load_dwordx4 v[50:53], v[50:51], off
	s_nop 0
	global_load_dwordx4 v[54:57], v[54:55], off
; #define LASP __attribute__((address_space(3)))
; template <int DQK>
; __device__ __forceinline__ void flash_item(unsigned char* smem, const bf16_t* Q, int qs, const bf16_t* K0, const bf16_t* V0, int n0, const bf16_t* K1, const bf16_t* V1, int n1, int ks, int vs, bf16_t* Oo, int os, float shift) {
;     ...
; #pragma unroll
;         for (int kk = 0; kk < NKK; ++kk) {
; #pragma unroll
;             for (int kg = 0; kg < NKG; ++kg) {
;                 const bf16x8_t kf = *(const LASP bf16x8_t*)(ls + (kg * 16 + fr) * KR + (kk * 32 + fq * 8) * 2);
;                 s[kg][0] = __builtin_amdgcn_mfma_f32_16x16x32_bf16(kf, qf[0][kk], s[kg][0], 0, 0, 0);
;                 s[kg][1] = __builtin_amdgcn_mfma_f32_16x16x32_bf16(kf, qf[1][kk], s[kg][1], 0, 0, 0);
;             }
;             asm volatile("" ::: "memory");
;         }
;         if (t + 1 < ntiles) FL_LOAD((t + 1) * KT);
.Lmla_ld_skip:
	ds_read_b128 v[232:235], v162 offset:6720
	s_waitcnt lgkmcnt(10)
	v_mfma_f32_16x16x32_bf16 v[86:89], v[180:183], v[14:17], v[82:85]
	v_mfma_f32_16x16x32_bf16 v[78:81], v[180:183], v[18:21], v[82:85]
	ds_read_b128 v[180:183], v162 offset:10048
	s_waitcnt lgkmcnt(10)
	v_mfma_f32_16x16x32_bf16 v[94:97], v[184:187], v[14:17], v[82:85]
	v_mfma_f32_16x16x32_bf16 v[90:93], v[184:187], v[18:21], v[82:85]
	ds_read_b128 v[184:187], v162 offset:13376
	s_waitcnt lgkmcnt(10)
	v_mfma_f32_16x16x32_bf16 v[102:105], v[188:191], v[14:17], v[82:85]
	v_mfma_f32_16x16x32_bf16 v[98:101], v[188:191], v[18:21], v[82:85]
	ds_read_b128 v[188:191], v162 offset:16704
	s_waitcnt lgkmcnt(10)
	v_mfma_f32_16x16x32_bf16 v[110:113], v[192:195], v[14:17], v[82:85]
	v_mfma_f32_16x16x32_bf16 v[106:109], v[192:195], v[18:21], v[82:85]
	ds_read_b128 v[192:195], v162 offset:20032
	s_waitcnt lgkmcnt(10)
	v_mfma_f32_16x16x32_bf16 v[118:121], v[196:199], v[14:17], v[82:85]
	v_mfma_f32_16x16x32_bf16 v[114:117], v[196:199], v[18:21], v[82:85]
	ds_read_b128 v[196:199], v162 offset:23360
	s_waitcnt lgkmcnt(10)
	v_mfma_f32_16x16x32_bf16 v[126:129], v[200:203], v[14:17], v[82:85]
	v_mfma_f32_16x16x32_bf16 v[122:125], v[200:203], v[18:21], v[82:85]
	ds_read_b128 v[200:203], v162 offset:128
	s_waitcnt lgkmcnt(10)
	v_mfma_f32_16x16x32_bf16 v[134:137], v[204:207], v[14:17], v[82:85]
	v_mfma_f32_16x16x32_bf16 v[130:133], v[204:207], v[18:21], v[82:85]
	ds_read_b128 v[204:207], v162 offset:3456
	s_waitcnt lgkmcnt(10)
	v_mfma_f32_16x16x32_bf16 v[146:149], v[212:215], v[14:17], v[82:85]
	v_mfma_f32_16x16x32_bf16 v[82:85], v[212:215], v[18:21], v[82:85]
	ds_read_b128 v[212:215], v162 offset:10112
	s_waitcnt lgkmcnt(10)
	v_mfma_f32_16x16x32_bf16 v[86:89], v[224:227], v[22:25], v[86:89]
	v_mfma_f32_16x16x32_bf16 v[78:81], v[224:227], v[30:33], v[78:81]
	ds_read_b128 v[224:227], v162 offset:6784
	s_waitcnt lgkmcnt(10)
	v_mfma_f32_16x16x32_bf16 v[94:97], v[228:231], v[22:25], v[94:97]
	v_mfma_f32_16x16x32_bf16 v[90:93], v[228:231], v[30:33], v[90:93]
	ds_read_b128 v[228:231], v162 offset:13440
	s_waitcnt lgkmcnt(10)
	v_mfma_f32_16x16x32_bf16 v[150:153], v[232:235], v[22:25], v[102:105]
	s_nop 2
	ds_read_b128 v[236:239], v162 offset:16768
	s_waitcnt lgkmcnt(10)
	v_mfma_f32_16x16x32_bf16 v[110:113], v[180:183], v[22:25], v[110:113]
	v_mfma_f32_16x16x32_bf16 v[106:109], v[180:183], v[30:33], v[106:109]
	ds_read_b128 v[180:183], v162 offset:20096
	s_waitcnt lgkmcnt(10)
	v_mfma_f32_16x16x32_bf16 v[118:121], v[184:187], v[22:25], v[118:121]
	v_mfma_f32_16x16x32_bf16 v[114:117], v[184:187], v[30:33], v[114:117]
	ds_read_b128 v[184:187], v162 offset:23424
	s_waitcnt lgkmcnt(10)
	v_mfma_f32_16x16x32_bf16 v[164:167], v[188:191], v[22:25], v[126:129]
	v_mfma_f32_16x16x32_bf16 v[122:125], v[188:191], v[30:33], v[122:125]
	s_waitcnt lgkmcnt(9)
	v_mfma_f32_16x16x32_bf16 v[168:171], v[192:195], v[22:25], v[134:137]
	v_mfma_f32_16x16x32_bf16 v[172:175], v[192:195], v[30:33], v[130:133]
	s_waitcnt lgkmcnt(8)
	v_mfma_f32_16x16x32_bf16 v[176:179], v[196:199], v[30:33], v[82:85]
	s_nop 2
	v_mfma_f32_16x16x32_bf16 v[98:101], v[232:235], v[30:33], v[98:101]
	v_mfma_f32_16x16x32_bf16 v[146:149], v[196:199], v[22:25], v[146:149]
	s_waitcnt lgkmcnt(7)
	v_mfma_f32_16x16x32_bf16 v[138:141], v[200:203], v[34:37], v[86:89]
	v_mfma_f32_16x16x32_bf16 v[102:105], v[200:203], v[26:29], v[78:81]
	s_nop 1
	s_waitcnt lgkmcnt(6)
	v_mfma_f32_16x16x32_bf16 v[134:137], v[204:207], v[34:37], v[94:97]
	s_nop 2
	v_mfma_f32_16x16x32_bf16 v[86:89], v[204:207], v[26:29], v[90:93]
	s_waitcnt lgkmcnt(5)
	v_mfma_f32_16x16x32_bf16 v[126:129], v[212:215], v[34:37], v[110:113]
	v_mfma_f32_16x16x32_bf16 v[90:93], v[212:215], v[26:29], v[106:109]
	s_waitcnt lgkmcnt(4)
	v_mfma_f32_16x16x32_bf16 v[130:133], v[224:227], v[34:37], v[150:153]
	v_mfma_f32_16x16x32_bf16 v[78:81], v[224:227], v[26:29], v[98:101]
	s_waitcnt lgkmcnt(3)
	v_mfma_f32_16x16x32_bf16 v[110:113], v[228:231], v[34:37], v[118:121]
	s_waitcnt lgkmcnt(2)
	v_mfma_f32_16x16x32_bf16 v[118:121], v[236:239], v[34:37], v[164:167]
	v_mfma_f32_16x16x32_bf16 v[98:101], v[236:239], v[26:29], v[122:125]
	v_mfma_f32_16x16x32_bf16 v[82:85], v[228:231], v[26:29], v[114:117]
	s_waitcnt lgkmcnt(1)
	v_mfma_f32_16x16x32_bf16 v[114:117], v[180:183], v[34:37], v[168:171]
	v_mfma_f32_16x16x32_bf16 v[94:97], v[180:183], v[26:29], v[172:175]
	s_waitcnt lgkmcnt(0)
	v_mfma_f32_16x16x32_bf16 v[122:125], v[184:187], v[34:37], v[146:149]
	v_mfma_f32_16x16x32_bf16 v[106:109], v[184:187], v[26:29], v[176:179]
	s_branch .LBB0_831
